# counted wait (lever 1) in the XCD barrier: the XCD-last leader issues its invalidate behind the cross-XCD arrival atomic and waits vmcnt(1) for the atomic only; the invalidate stays in flight until th
# baseline (speedup 1.0000x reference)
; DI unsigned xb_ld(unsigned* p)              { return __hip_atomic_load(p, __ATOMIC_RELAXED, __HIP_MEMORY_SCOPE_AGENT); }
; DI unsigned xb_add(unsigned* p, unsigned v) { return __hip_atomic_fetch_add(p, v, __ATOMIC_RELAXED, __HIP_MEMORY_SCOPE_AGENT); }
; #define XB_SPIN(cond, bar) do { unsigned _sp = 0; while (cond) { __builtin_amdgcn_s_sleep(1); \
;     if ((++_sp & 255u) == 0u) { if (xb_ld(&(bar)[XB_TMO])) break; if (_sp > XB_SPIN_CAP) { atomicAdd(&(bar)[XB_TMO], 1u); break; } } } } while (0)
; DI void xcd_barrier(const XcdBarrier& b) {
;     ...
;         const unsigned old = xb_add(&bar[XB_XSUB(b.x)], 1u);
;         const unsigned gen = old / nloc;
;         if (old + 1u == (gen + 1u) * nloc) {
;             __builtin_amdgcn_fence(__ATOMIC_RELEASE, "agent");
;             asm volatile("s_waitcnt vmcnt(0)" ::: "memory");
;             const unsigned og = xb_add(&bar[XB_TOP], 1u);
;             const unsigned tg = og / nx;
;             if (og + 1u == (tg + 1u) * nx) xb_add(&bar[XB_TOPGEN], 1u);
;             else XB_SPIN(xb_ld(&bar[XB_TOPGEN]) == tg, bar);
;             __builtin_amdgcn_fence(__ATOMIC_ACQUIRE, "agent");
;             xb_add(&bar[XB_XGEN(b.x)], 1u);
.LBB0_188:
	s_andn2_saveexec_b64 s[4:5], s[4:5]
	s_cbranch_execz .LBB0_208
	s_mov_b64 s[6:7], exec
	buffer_wbl2 sc1
	s_waitcnt lgkmcnt(0)
	s_waitcnt vmcnt(0)
	v_mbcnt_lo_u32_b32 v1, s6, 0
	v_mbcnt_hi_u32_b32 v1, s7, v1
	v_cmp_eq_u32_e32 vcc, 0, v1
	s_and_saveexec_b64 s[8:9], vcc
	s_cbranch_execz .LBB0_191
	s_bcnt1_i32_b64 s0, s[6:7]
	v_mov_b32_e32 v3, s0
	v_readlane_b32 s0, v253, 45
	v_readlane_b32 s1, v253, 46
	s_nop 4
	global_atomic_add v3, v0, v3, s[0:1] sc0
	buffer_inv sc1
.LBB0_191:
	s_or_b64 exec, exec, s[8:9]
	v_cvt_f32_u32_e32 v5, v2
	s_waitcnt vmcnt(1)
	v_readfirstlane_b32 s0, v3
	s_mov_b64 s[8:9], -1
	v_rcp_iflag_f32_e32 v5, v5
	v_add_u32_e32 v1, s0, v1
	v_add_u32_e32 v6, 1, v1
	v_readlane_b32 s0, v253, 47
	v_mul_f32_e32 v3, 0x4f7ffffe, v5
	v_cvt_u32_f32_e32 v3, v3
	v_sub_u32_e32 v5, 0, v2
	v_readlane_b32 s1, v253, 48
	v_mul_lo_u32 v5, v5, v3
	v_mul_hi_u32 v5, v3, v5
	v_add_u32_e32 v3, v3, v5
	v_mul_hi_u32 v3, v1, v3
	v_mul_lo_u32 v5, v3, v2
	v_sub_u32_e32 v1, v1, v5
	v_add_u32_e32 v7, 1, v3
	v_cmp_ge_u32_e32 vcc, v1, v2
	v_sub_u32_e32 v5, v1, v2
	s_nop 0
	v_cndmask_b32_e32 v3, v3, v7, vcc
	v_cndmask_b32_e32 v1, v1, v5, vcc
	v_add_u32_e32 v5, 1, v3
	v_cmp_ge_u32_e32 vcc, v1, v2
	s_nop 1
	v_cndmask_b32_e32 v1, v3, v5, vcc
	v_mul_lo_u32 v3, v2, v1
	v_add_u32_e32 v2, v3, v2
	v_cmp_ne_u32_e32 vcc, v6, v2
	v_mov_b64_e32 v[2:3], s[0:1]
	s_and_saveexec_b64 s[6:7], vcc
	s_cbranch_execz .LBB0_203
	v_readlane_b32 s0, v253, 47
	v_readlane_b32 s1, v253, 48
	s_mov_b64 s[10:11], 0
	s_nop 3
	global_load_dword v2, v0, s[0:1] sc1
	s_waitcnt vmcnt(0)
	v_cmp_eq_u32_e32 vcc, v2, v1
	s_and_saveexec_b64 s[8:9], vcc
	s_cbranch_execz .LBB0_202
	s_mov_b32 s0, 1
	s_branch .LBB0_195

; DI unsigned xb_ld(unsigned* p)              { return __hip_atomic_load(p, __ATOMIC_RELAXED, __HIP_MEMORY_SCOPE_AGENT); }
; DI unsigned xb_add(unsigned* p, unsigned v) { return __hip_atomic_fetch_add(p, v, __ATOMIC_RELAXED, __HIP_MEMORY_SCOPE_AGENT); }
; #define XB_SPIN(cond, bar) do { unsigned _sp = 0; while (cond) { __builtin_amdgcn_s_sleep(1); \
;     if ((++_sp & 255u) == 0u) { if (xb_ld(&(bar)[XB_TMO])) break; if (_sp > XB_SPIN_CAP) { atomicAdd(&(bar)[XB_TMO], 1u); break; } } } } while (0)
; DI void xcd_barrier(const XcdBarrier& b) {
;     ...
;         const unsigned old = xb_add(&bar[XB_XSUB(b.x)], 1u);
;         const unsigned gen = old / nloc;
;         if (old + 1u == (gen + 1u) * nloc) {
;             __builtin_amdgcn_fence(__ATOMIC_RELEASE, "agent");
;             asm volatile("s_waitcnt vmcnt(0)" ::: "memory");
;             const unsigned og = xb_add(&bar[XB_TOP], 1u);
;             const unsigned tg = og / nx;
;             if (og + 1u == (tg + 1u) * nx) xb_add(&bar[XB_TOPGEN], 1u);
;             else XB_SPIN(xb_ld(&bar[XB_TOPGEN]) == tg, bar);
.LBB0_318:
	s_or_b64 exec, exec, s[8:9]
	s_waitcnt vmcnt(1)
	v_readfirstlane_b32 s0, v3
	v_sub_u32_e32 v5, 0, v2
	s_mov_b64 s[8:9], -1
	v_add_u32_e32 v3, s0, v1
	v_cvt_f32_u32_e32 v1, v2
	v_readlane_b32 s0, v253, 47
	v_readlane_b32 s1, v253, 48
	v_rcp_iflag_f32_e32 v1, v1
	s_nop 0
	v_mul_f32_e32 v1, 0x4f7ffffe, v1
	v_cvt_u32_f32_e32 v1, v1
	v_mul_lo_u32 v5, v5, v1
	v_mul_hi_u32 v5, v1, v5
	v_add_u32_e32 v1, v1, v5
	v_mul_hi_u32 v1, v3, v1
	v_mul_lo_u32 v5, v1, v2
	v_sub_u32_e32 v5, v3, v5
	v_cmp_ge_u32_e32 vcc, v5, v2
	v_add_u32_e32 v6, 1, v1
	v_add_u32_e32 v3, 1, v3
	v_cndmask_b32_e32 v1, v1, v6, vcc
	v_sub_u32_e32 v6, v5, v2
	v_cndmask_b32_e32 v5, v5, v6, vcc
	v_cmp_ge_u32_e32 vcc, v5, v2
	v_add_u32_e32 v5, 1, v1
	s_nop 0
	v_cndmask_b32_e32 v1, v1, v5, vcc
	v_mul_lo_u32 v5, v2, v1
	v_add_u32_e32 v2, v5, v2
	v_cmp_ne_u32_e32 vcc, v3, v2
	v_mov_b64_e32 v[2:3], s[0:1]
	s_and_saveexec_b64 s[6:7], vcc
	s_cbranch_execz .LBB0_330
	v_readlane_b32 s0, v253, 47
	v_readlane_b32 s1, v253, 48
	s_mov_b64 s[10:11], 0
	s_nop 3
	global_load_dword v2, v0, s[0:1] sc1
	s_waitcnt vmcnt(0)
	v_cmp_eq_u32_e32 vcc, v2, v1
	s_and_saveexec_b64 s[8:9], vcc
	s_cbranch_execz .LBB0_329
	s_mov_b32 s0, 1
	s_branch .LBB0_322

; DI unsigned xb_ld(unsigned* p)              { return __hip_atomic_load(p, __ATOMIC_RELAXED, __HIP_MEMORY_SCOPE_AGENT); }
; DI unsigned xb_add(unsigned* p, unsigned v) { return __hip_atomic_fetch_add(p, v, __ATOMIC_RELAXED, __HIP_MEMORY_SCOPE_AGENT); }
; #define XB_SPIN(cond, bar) do { unsigned _sp = 0; while (cond) { __builtin_amdgcn_s_sleep(1); \
;     if ((++_sp & 255u) == 0u) { if (xb_ld(&(bar)[XB_TMO])) break; if (_sp > XB_SPIN_CAP) { atomicAdd(&(bar)[XB_TMO], 1u); break; } } } } while (0)
; DI void xcd_barrier(const XcdBarrier& b) {
;     ...
;         const unsigned old = xb_add(&bar[XB_XSUB(b.x)], 1u);
;         const unsigned gen = old / nloc;
;         if (old + 1u == (gen + 1u) * nloc) {
;             __builtin_amdgcn_fence(__ATOMIC_RELEASE, "agent");
;             asm volatile("s_waitcnt vmcnt(0)" ::: "memory");
;             const unsigned og = xb_add(&bar[XB_TOP], 1u);
;             const unsigned tg = og / nx;
;             if (og + 1u == (tg + 1u) * nx) xb_add(&bar[XB_TOPGEN], 1u);
;             else XB_SPIN(xb_ld(&bar[XB_TOPGEN]) == tg, bar);
;             __builtin_amdgcn_fence(__ATOMIC_ACQUIRE, "agent");
;             xb_add(&bar[XB_XGEN(b.x)], 1u);
.LBB0_373:
	s_andn2_saveexec_b64 s[0:1], s[4:5]
	s_cbranch_execz .LBB0_393
	s_mov_b64 s[4:5], exec
	buffer_wbl2 sc1
	s_waitcnt lgkmcnt(0)
	s_waitcnt vmcnt(0)
	v_mbcnt_lo_u32_b32 v1, s4, 0
	v_mbcnt_hi_u32_b32 v1, s5, v1
	v_cmp_eq_u32_e32 vcc, 0, v1
	s_and_saveexec_b64 s[6:7], vcc
	s_cbranch_execz .LBB0_376
	s_bcnt1_i32_b64 s0, s[4:5]
	v_mov_b32_e32 v3, s0
	v_readlane_b32 s0, v253, 45
	v_readlane_b32 s1, v253, 46
	s_nop 4
	global_atomic_add v3, v0, v3, s[0:1] sc0
	buffer_inv sc1
.LBB0_376:
	s_or_b64 exec, exec, s[6:7]
	s_waitcnt vmcnt(1)
	v_readfirstlane_b32 s0, v3
	v_sub_u32_e32 v5, 0, v2
	s_mov_b64 s[6:7], -1
	v_add_u32_e32 v3, s0, v1
	v_cvt_f32_u32_e32 v1, v2
	v_readlane_b32 s0, v253, 47
	v_readlane_b32 s1, v253, 48
	v_rcp_iflag_f32_e32 v1, v1
	s_nop 0
	v_mul_f32_e32 v1, 0x4f7ffffe, v1
	v_cvt_u32_f32_e32 v1, v1
	v_mul_lo_u32 v5, v5, v1
	v_mul_hi_u32 v5, v1, v5
	v_add_u32_e32 v1, v1, v5
	v_mul_hi_u32 v1, v3, v1
	v_mul_lo_u32 v5, v1, v2
	v_sub_u32_e32 v5, v3, v5
	v_cmp_ge_u32_e32 vcc, v5, v2
	v_add_u32_e32 v6, 1, v1
	v_add_u32_e32 v3, 1, v3
	v_cndmask_b32_e32 v1, v1, v6, vcc
	v_sub_u32_e32 v6, v5, v2
	v_cndmask_b32_e32 v5, v5, v6, vcc
	v_cmp_ge_u32_e32 vcc, v5, v2
	v_add_u32_e32 v5, 1, v1
	s_nop 0
	v_cndmask_b32_e32 v1, v1, v5, vcc
	v_mul_lo_u32 v5, v2, v1
	v_add_u32_e32 v2, v5, v2
	v_cmp_ne_u32_e32 vcc, v3, v2
	v_mov_b64_e32 v[2:3], s[0:1]
	s_and_saveexec_b64 s[4:5], vcc
	s_cbranch_execz .LBB0_388
	v_readlane_b32 s0, v253, 47
	v_readlane_b32 s1, v253, 48
	s_mov_b64 s[8:9], 0
	s_nop 3
	global_load_dword v2, v0, s[0:1] sc1
	s_waitcnt vmcnt(0)
	v_cmp_eq_u32_e32 vcc, v2, v1
	s_and_saveexec_b64 s[6:7], vcc
	s_cbranch_execz .LBB0_387
	s_mov_b32 s0, 1
	s_branch .LBB0_380
